# attention loop: packed f32 adds for max subtraction and row sum; first-half K fragments requested behind the tile barrier (prompt tiles)
# baseline (speedup 1.0000x reference)
; __device__ __forceinline__ void attn_item(const P& p, Frame& F, const bool is_s, const int b, const int g, const int c) {
;     ...
;         for (int i = 0; i < ntiles; ++i) {
;             const void* kp; const void* vp; int pitch, nvalid = 64, kp0, kstride = 1, wl = HUGE_W, mode = 2; bool lv = qvalid;
;             if (ph < 2) { kp = kc_k + (size_t)(64 * i) * 512; vp = kc_v + (size_t)(64 * i) * 512; pitch = 512; mode = 1; kp0 = 2048 * i + 31; kstride = 32; }
.LBB0_2013:
	s_mov_b32 s98, 0
	v_cndmask_b32_e64 v1, 0, 1, s[18:19]
	s_mov_b64 s[96:97], -1
	v_cmp_ne_u32_e64 s[10:11], 1, v1
	s_andn2_b64 vcc, exec, s[18:19]
	s_mov_b64 s[14:15], -1
	s_cbranch_vccnz .LBB0_2015
	s_lshl_b32 s44, s33, 6
	s_lshl_b64 s[6:7], s[44:45], 11
	s_add_u32 s0, s53, s6
	s_addc_u32 s1, s68, s7
	s_add_u32 s6, s69, s6
	s_addc_u32 s7, s3, s7
	s_lshl_b32 s14, s33, 11
	s_or_b32 s25, s14, 31
	s_mov_b64 s[14:15], 0

; #define LAS __attribute__((address_space(3)))
; template <int MODE> ...
;     ...
;         { const LAS unsigned char* ka = KT + (32 * nt + ql) * KT_PITCH + 16 * half;
; #pragma unroll
;           for (int kg = 0; kg < 2; ++kg) { bf16x8 kf[4];
; #pragma unroll
;               for (int ks = 0; ks < 4; ++ks) kf[ks] = *(const LAS bf16x8*)(ka + 32 * (4 * kg + ks));
; __device__ __forceinline__ void attn_item(const P& p, Frame& F, const bool is_s, const int b, const int g, const int c) {
;     ...
;             } else if (mode == 0) {
;                 if (i == 0) { __syncthreads(); tile_load(tr, (const bf16*)kp, (const bf16*)vp, pitch, tid); tile_store(F, tr, tid, 0); if (ntiles > 1) tile_load(tr, (const bf16*)kp + (size_t)64 * pitch, (const bf16*)vp + 128 * 64, pitch, tid); }
;                 __syncthreads();
;                 if (i + 1 < ntiles) { tile_store(F, tr, tid, ((i + 1) & 1) * A_BUF2); if (i + 2 < ntiles) tile_load(tr, (const bf16*)kp + (size_t)128 * pitch, (const bf16*)vp + 2 * 128 * 64, pitch, tid); }
.LBB0_2057:
	s_add_i32 s6, s33, 1
	s_cmp_ge_i32 s6, s2
	s_waitcnt lgkmcnt(0)
	s_barrier
	s_bitcmp1_b32 s33, 0
	s_cselect_b32 s98, 0x19f00, 0
	v_mad_u32_u24 v113, v227, s54, v237
	v_add_u32_e32 v113, s98, v113
	ds_read_b128 v[114:117], v113
	ds_read_b128 v[118:121], v113 offset:32
	ds_read_b128 v[122:125], v113 offset:64
	ds_read_b128 v[126:129], v113 offset:96
	ds_read_b128 v[130:133], v113 offset:128
	ds_read_b128 v[134:137], v113 offset:160
	ds_read_b128 v[138:141], v113 offset:192
	ds_read_b128 v[142:145], v113 offset:224
	s_mov_b32 s98, 1
	s_cmp_ge_i32 s6, s2
	s_cbranch_scc1 .LBB0_2060
	s_bitcmp1_b32 s6, 0
	s_cselect_b32 s6, 0x19f00, 0
	v_ashrrev_i32_e32 v101, 3, v108
	v_lshlrev_b32_e32 v102, 5, v108
	s_add_i32 s6, s6, 0
	v_mul_lo_u32 v100, v101, s54
	v_and_b32_e32 v2, 0xe0, v102
	v_add3_u32 v100, s6, v100, v2
	s_waitcnt vmcnt(2)
	ds_write_b128 v100, v[8:11]
	ds_write_b128 v100, v[4:7] offset:16
	v_lshrrev_b32_e32 v100, 2, v108
	s_movk_i32 s7, 0x88
	v_mul_lo_u32 v103, v100, s7
	v_and_b32_e32 v100, 0x60, v102
	v_add3_u32 v102, s6, v103, v100
	s_add_i32 s6, s33, 2
	v_add_u32_e32 v103, 0x4400, v102
	v_add_u32_e32 v102, 0x4410, v102
	s_cmp_ge_i32 s6, s2
	s_waitcnt vmcnt(1)
	ds_write2_b64 v103, v[194:195], v[196:197] offset1:1
	s_waitcnt vmcnt(0)
	ds_write2_b64 v102, v[12:13], v[14:15] offset1:1
	s_cbranch_scc1 .LBB0_2060
	v_lshlrev_b32_e32 v12, 4, v108
	v_and_b32_e32 v12, 0xffffffc0, v12
	v_ashrrev_i32_e32 v13, 31, v12
	s_lshl_b32 s44, s62, 8
	v_mad_i64_i32 v[6:7], s[6:7], v101, s62, 0
	v_lshl_add_u64 v[12:13], v[12:13], 1, v[16:17]
	v_mov_b32_e32 v101, v3
	v_lshl_add_u64 v[4:5], v[98:99], 0, s[44:45]
	v_lshl_add_u64 v[12:13], v[12:13], 0, v[100:101]
	s_mov_b64 s[6:7], 0x8000
	v_lshl_add_u64 v[4:5], v[6:7], 1, v[4:5]
	v_lshl_add_u64 v[14:15], v[12:13], 0, s[6:7]
	v_add_co_u32_e32 v12, vcc, 0x8000, v12
	v_lshl_add_u64 v[8:9], v[4:5], 0, v[2:3]
	s_nop 0
	v_addc_co_u32_e32 v13, vcc, 0, v13, vcc
	global_load_dwordx4 v[4:7], v[8:9], off offset:16
	s_nop 0
	global_load_dwordx4 v[8:11], v[8:9], off
	s_nop 0
	global_load_dwordx4 v[194:197], v[12:13], off
	s_nop 0
	global_load_dwordx4 v[12:15], v[14:15], off offset:16

; #define LAS __attribute__((address_space(3)))
; #define MFMA32(a, b, c) __builtin_amdgcn_mfma_f32_32x32x16_bf16((a), (b), (c), 0, 0, 0)
; template <int MODE> ...
;     ...
;         { const LAS unsigned char* ka = KT + (32 * nt + ql) * KT_PITCH + 16 * half;
; #pragma unroll
;           for (int kg = 0; kg < 2; ++kg) { bf16x8 kf[4];
; #pragma unroll
;               for (int ks = 0; ks < 4; ++ks) kf[ks] = *(const LAS bf16x8*)(ka + 32 * (4 * kg + ks));
; #pragma unroll
;               for (int ks = 0; ks < 4; ++ks) st = MFMA32(kf[ks], qf[4 * kg + ks], st); } }
.LBB0_2107:
	s_lshl_b32 s26, s63, 5
	s_cmp_lg_u32 s63, 0
	s_cbranch_scc1 .Lattn_kready
	s_cmp_lg_u32 s98, 0
	s_cbranch_scc1 .Lattn_kready2
	v_or_b32_e32 v16, s26, v227
	v_mad_u32_u24 v16, v16, s54, v2
	ds_read_b128 v[82:85], v16
	ds_read_b128 v[86:89], v16 offset:32
	ds_read_b128 v[90:93], v16 offset:64
	ds_read_b128 v[94:97], v16 offset:96
	ds_read_b128 v[98:101], v16 offset:128
	ds_read_b128 v[102:105], v16 offset:160
	ds_read_b128 v[106:109], v16 offset:192
	ds_read_b128 v[110:113], v16 offset:224
	s_waitcnt lgkmcnt(7)
	v_mfma_f32_32x32x16_bf16 v[146:161], v[82:85], v[166:169], 0
	s_waitcnt lgkmcnt(6)
	v_mfma_f32_32x32x16_bf16 v[146:161], v[86:89], v[162:165], v[146:161]
	s_waitcnt lgkmcnt(5)
	v_mfma_f32_32x32x16_bf16 v[146:161], v[90:93], v[174:177], v[146:161]
	s_waitcnt lgkmcnt(4)
	v_mfma_f32_32x32x16_bf16 v[146:161], v[94:97], v[170:173], v[146:161]
	s_waitcnt lgkmcnt(3)
	v_mfma_f32_32x32x16_bf16 v[146:161], v[98:101], v[182:185], v[146:161]
	s_waitcnt lgkmcnt(2)
	v_mfma_f32_32x32x16_bf16 v[146:161], v[102:105], v[178:181], v[146:161]
	s_waitcnt lgkmcnt(1)
	v_mfma_f32_32x32x16_bf16 v[146:161], v[106:109], v[190:193], v[146:161]
	s_waitcnt lgkmcnt(0)
	v_mfma_f32_32x32x16_bf16 v[146:161], v[110:113], v[186:189], v[146:161]
	s_branch .Lattn_qkdone
.Lattn_kready:
	s_waitcnt lgkmcnt(0)
	v_mfma_f32_32x32x16_bf16 v[146:161], v[82:85], v[166:169], 0
	v_mfma_f32_32x32x16_bf16 v[146:161], v[86:89], v[162:165], v[146:161]
	v_mfma_f32_32x32x16_bf16 v[146:161], v[90:93], v[174:177], v[146:161]
	v_mfma_f32_32x32x16_bf16 v[146:161], v[94:97], v[170:173], v[146:161]
	v_mfma_f32_32x32x16_bf16 v[146:161], v[98:101], v[182:185], v[146:161]
	v_mfma_f32_32x32x16_bf16 v[146:161], v[102:105], v[178:181], v[146:161]
	v_mfma_f32_32x32x16_bf16 v[146:161], v[106:109], v[190:193], v[146:161]
	v_mfma_f32_32x32x16_bf16 v[146:161], v[110:113], v[186:189], v[146:161]
	s_branch .Lattn_qkdone
.Lattn_kready2:
	s_waitcnt lgkmcnt(0)
	v_mfma_f32_32x32x16_bf16 v[146:161], v[114:117], v[166:169], 0
	v_mfma_f32_32x32x16_bf16 v[146:161], v[118:121], v[162:165], v[146:161]
	v_mfma_f32_32x32x16_bf16 v[146:161], v[122:125], v[174:177], v[146:161]
	v_mfma_f32_32x32x16_bf16 v[146:161], v[126:129], v[170:173], v[146:161]
	v_mfma_f32_32x32x16_bf16 v[146:161], v[130:133], v[182:185], v[146:161]
	v_mfma_f32_32x32x16_bf16 v[146:161], v[134:137], v[178:181], v[146:161]
	v_mfma_f32_32x32x16_bf16 v[146:161], v[138:141], v[190:193], v[146:161]
	v_mfma_f32_32x32x16_bf16 v[146:161], v[142:145], v[186:189], v[146:161]

; #define LAS __attribute__((address_space(3)))
; __device__ __forceinline__ unsigned pk2(float lo, float hi) { const bfx2 b = __builtin_convertvector((f32x2){lo, hi}, bfx2); return __builtin_bit_cast(unsigned, b); }
; #define MFMA32(a, b, c) __builtin_amdgcn_mfma_f32_32x32x16_bf16((a), (b), (c), 0, 0, 0)
; template <int MODE> ...
;     ...
;             float ls = 0.f; const float meff = lanevalid ? m : 3.0e30f;
; #pragma unroll
;             for (int r = 0; r < 16; ++r) { const float pv = __builtin_amdgcn_exp2f(st[r] - meff); st[r] = pv; ls += pv; }
;             l += ls;
; #pragma unroll
;             for (int s = 0; s < 2; ++s) {
;                 u32x4 pb; pb.x = pk2(st[8 * s + 0], st[8 * s + 1]); pb.y = pk2(st[8 * s + 2], st[8 * s + 3]); pb.z = pk2(st[8 * s + 4], st[8 * s + 5]); pb.w = pk2(st[8 * s + 6], st[8 * s + 7]);
;                 const bf16x8 bfrag = __builtin_bit_cast(bf16x8, pb);
;                 const LAS unsigned char* va = VT + ql * VT_PITCH + (32 * nt + 16 * s + 4 * half) * 2;
;                 s16x4 lo[4], hi[4];
; #pragma unroll
;                 for (int dt = 0; dt < 4; ++dt) { lo[dt] = *(const LAS s16x4*)(va + 32 * dt * VT_PITCH); hi[dt] = *(const LAS s16x4*)(va + 32 * dt * VT_PITCH + 16); }
; #pragma unroll
;                 for (int dt = 0; dt < 4; ++dt) { const bf16x8 afrag = __builtin_shufflevector(lo[dt], hi[dt], 0, 1, 2, 3, 4, 5, 6, 7); ot[dt] = MFMA32(afrag, bfrag, ot[dt]); }
;             }
.LBB0_2118:
	v_cndmask_b32_e64 v147, v225, v146, s[74:75]
	v_lshl_add_u32 v159, s63, 6, v244
	v_add_u32_e32 v156, 0x4000, v159
	v_add_u32_e32 v157, 0x5000, v159
	v_add_u32_e32 v158, 0x6000, v159
	v_add_u32_e32 v159, 0x7000, v159
	ds_read2_b64 v[114:117], v156 offset0:128 offset1:130
	ds_read2_b64 v[118:121], v157 offset0:160 offset1:162
	ds_read2_b64 v[122:125], v158 offset0:192 offset1:194
	ds_read2_b64 v[126:129], v159 offset0:224 offset1:226
	ds_read2_b64 v[130:133], v156 offset0:132 offset1:134
	ds_read2_b64 v[134:137], v157 offset0:164 offset1:166
	ds_read2_b64 v[138:141], v158 offset0:196 offset1:198
	ds_read2_b64 v[142:145], v159 offset0:228 offset1:230
	v_pk_add_f32 v[16:17], v[16:17], v[146:147] op_sel:[0,1] op_sel_hi:[1,1] neg_lo:[0,1] neg_hi:[0,1]
	v_pk_add_f32 v[206:207], v[206:207], v[146:147] op_sel:[0,1] op_sel_hi:[1,1] neg_lo:[0,1] neg_hi:[0,1]
	v_pk_add_f32 v[210:211], v[210:211], v[146:147] op_sel:[0,1] op_sel_hi:[1,1] neg_lo:[0,1] neg_hi:[0,1]
	v_pk_add_f32 v[208:209], v[208:209], v[146:147] op_sel:[0,1] op_sel_hi:[1,1] neg_lo:[0,1] neg_hi:[0,1]
	v_exp_f32_e32 v16, v16
	v_exp_f32_e32 v17, v17
	v_exp_f32_e32 v206, v206
	v_exp_f32_e32 v207, v207
	v_exp_f32_e32 v210, v210
	v_exp_f32_e32 v211, v211
	v_exp_f32_e32 v208, v208
	v_exp_f32_e32 v209, v209
	v_pk_add_f32 v[212:213], v[212:213], v[146:147] op_sel:[0,1] op_sel_hi:[1,1] neg_lo:[0,1] neg_hi:[0,1]
	v_cvt_pk_bf16_f32 v152, v16, v17
	v_cvt_pk_bf16_f32 v153, v206, v207
	v_cvt_pk_bf16_f32 v154, v210, v211
	v_cvt_pk_bf16_f32 v155, v208, v209
	v_exp_f32_e32 v212, v212
	s_waitcnt lgkmcnt(7)
	v_mfma_f32_32x32x16_bf16 v[66:81], v[114:117], v[152:155], v[66:81]
	v_exp_f32_e32 v213, v213
	v_pk_add_f32 v[214:215], v[214:215], v[146:147] op_sel:[0,1] op_sel_hi:[1,1] neg_lo:[0,1] neg_hi:[0,1]
	v_exp_f32_e32 v214, v214
	v_exp_f32_e32 v215, v215
	s_waitcnt lgkmcnt(6)
	v_mfma_f32_32x32x16_bf16 v[50:65], v[118:121], v[152:155], v[50:65]
	v_pk_add_f32 v[216:217], v[216:217], v[146:147] op_sel:[0,1] op_sel_hi:[1,1] neg_lo:[0,1] neg_hi:[0,1]
	v_exp_f32_e32 v216, v216
	v_exp_f32_e32 v217, v217
	s_waitcnt lgkmcnt(5)
	v_mfma_f32_32x32x16_bf16 v[34:49], v[122:125], v[152:155], v[34:49]
	v_pk_add_f32 v[218:219], v[218:219], v[146:147] op_sel:[0,1] op_sel_hi:[1,1] neg_lo:[0,1] neg_hi:[0,1]
	v_exp_f32_e32 v218, v218
	v_exp_f32_e32 v219, v219
	s_waitcnt lgkmcnt(4)
	v_mfma_f32_32x32x16_bf16 v[18:33], v[126:129], v[152:155], v[18:33]
	v_cvt_pk_bf16_f32 v148, v212, v213
	v_cvt_pk_bf16_f32 v149, v214, v215
	v_cvt_pk_bf16_f32 v150, v216, v217
	s_cmp_lg_u32 s63, 0
	s_cbranch_scc1 .Lattn_tail_b
	v_or_b32_e32 v160, 32, v227
	v_mad_u32_u24 v160, v160, s54, v2
	ds_read_b128 v[82:85], v160
	ds_read_b128 v[86:89], v160 offset:32
	ds_read_b128 v[90:93], v160 offset:64
	ds_read_b128 v[94:97], v160 offset:96
	ds_read_b128 v[98:101], v160 offset:128
	ds_read_b128 v[102:105], v160 offset:160
	ds_read_b128 v[106:109], v160 offset:192
	ds_read_b128 v[110:113], v160 offset:224
	v_cvt_pk_bf16_f32 v151, v218, v219
	v_pk_add_f32 v[16:17], v[16:17], v[206:207]
	v_pk_add_f32 v[16:17], v[16:17], v[210:211]
	s_waitcnt lgkmcnt(11)
	v_mfma_f32_32x32x16_bf16 v[66:81], v[130:133], v[148:151], v[66:81]
	v_pk_add_f32 v[16:17], v[16:17], v[208:209]
	v_pk_add_f32 v[16:17], v[16:17], v[212:213]
	s_waitcnt lgkmcnt(10)
	v_mfma_f32_32x32x16_bf16 v[50:65], v[134:137], v[148:151], v[50:65]
	v_pk_add_f32 v[16:17], v[16:17], v[214:215]
	v_pk_add_f32 v[16:17], v[16:17], v[216:217]
	s_waitcnt lgkmcnt(9)
	v_mfma_f32_32x32x16_bf16 v[34:49], v[138:141], v[148:151], v[34:49]
	v_pk_add_f32 v[16:17], v[16:17], v[218:219]
	v_add_f32_e32 v16, v16, v17
	v_add_f32_e32 v243, v243, v16
	s_xor_b64 s[26:27], s[46:47], -1
	s_mov_b32 s63, 1
	s_andn2_b64 vcc, exec, s[26:27]
	s_mov_b64 s[46:47], 0
	s_waitcnt lgkmcnt(8)
	v_mfma_f32_32x32x16_bf16 v[18:33], v[142:145], v[148:151], v[18:33]
	v_mov_b32_e32 v245, v146
	s_branch .LBB0_2107
.Lattn_tail_b:
	v_cvt_pk_bf16_f32 v151, v218, v219
	v_pk_add_f32 v[16:17], v[16:17], v[206:207]
	v_pk_add_f32 v[16:17], v[16:17], v[210:211]
	s_waitcnt lgkmcnt(3)
	v_mfma_f32_32x32x16_bf16 v[66:81], v[130:133], v[148:151], v[66:81]
	v_pk_add_f32 v[16:17], v[16:17], v[208:209]
	v_pk_add_f32 v[16:17], v[16:17], v[212:213]
	s_waitcnt lgkmcnt(2)
	v_mfma_f32_32x32x16_bf16 v[50:65], v[134:137], v[148:151], v[50:65]
	v_pk_add_f32 v[16:17], v[16:17], v[214:215]
	v_pk_add_f32 v[16:17], v[16:17], v[216:217]
	s_waitcnt lgkmcnt(1)
	v_mfma_f32_32x32x16_bf16 v[34:49], v[138:141], v[148:151], v[34:49]
	v_pk_add_f32 v[16:17], v[16:17], v[218:219]
	v_add_f32_e32 v16, v16, v17
	v_add_f32_e32 v243, v243, v16
	s_xor_b64 s[26:27], s[46:47], -1
	s_mov_b32 s63, 1
	s_andn2_b64 vcc, exec, s[26:27]
	s_mov_b64 s[46:47], 0
	s_waitcnt lgkmcnt(0)
	v_mfma_f32_32x32x16_bf16 v[18:33], v[142:145], v[148:151], v[18:33]
	s_branch .Lattn_m0_exit
